# attention MODE0 steady loop: K/V LDS-DMA addresses as SGPR base + 32-bit lane offsets (removes four 64-bit VALU adds per two steps)
# speedup vs baseline: 1.0271x; 1.0116x over previous
.LBB0_796:
	v_lshlrev_b32_e32 v53, 1, v52
	v_lshlrev_b32_e32 v52, 4, v52
	v_and_b32_e32 v214, 32, v53
	v_and_b32_e32 v52, 0xc0, v52
	v_lshl_or_b32 v213, v209, 8, v52
	v_add_u32_e32 v52, 0, v214
	v_add3_u32 v219, v52, v211, v213
	v_max3_f32 v52, v36, v37, v20
	v_max3_f32 v53, v38, v39, v21
	s_and_b32 s0, s22, 0x3fffffc0
	v_max3_f32 v52, v52, v22, v23
	v_max3_f32 v53, v53, v42, v43
	s_lshl_b32 s0, s0, 2
	v_max3_f32 v52, v52, v40, v41
	v_max3_f32 v53, v53, v26, v27
	s_add_i32 s1, s64, 0x100
	v_max3_f32 v52, v52, v24, v25
	v_max3_f32 v53, v53, v46, v47
	s_add_i32 s53, s0, 0
	v_max3_f32 v52, v52, v44, v45
	v_max3_f32 v53, v53, v30, v31
	s_lshr_b32 s48, s1, 6
	v_max3_f32 v52, v52, v28, v29
	v_max3_f32 v53, v53, v50, v51
	s_mov_b64 s[22:23], 0x60000
	v_max3_f32 v52, v52, v48, v49
	v_max3_f32 v53, v53, v34, v35
	s_cmp_lg_u32 0, -1
	v_max3_f32 v52, v52, v32, v33
	s_mov_b64 s[10:11], 0x20000
	v_max_f32_e32 v52, v52, v53
	v_lshl_add_u64 v[190:191], v[84:85], 0, s[10:11]
	v_mov_b32_e32 v53, v52
	s_nop 1
	v_permlane32_swap_b32_e32 v52, v53
	v_max_f32_e32 v52, v52, v53
	s_mov_b32 s0, 1
	v_max_f32_e32 v52, v52, v228
	s_mov_b32 s24, 0
	v_add_f32_e32 v217, v3, v52
	v_sub_f32_e32 v53, v36, v52
	v_sub_f32_e32 v54, v37, v52
	v_sub_f32_e32 v55, v38, v52
	v_sub_f32_e32 v56, v39, v52
	v_sub_f32_e32 v57, v40, v52
	s_nop 0
	v_xor_b32_e32 v36, 0x80000000, v217
	v_sub_f32_e32 v58, v41, v52
	v_sub_f32_e32 v59, v42, v52
	v_sub_f32_e32 v60, v43, v52
	v_sub_f32_e32 v61, v44, v52
	v_sub_f32_e32 v62, v45, v52
	v_sub_f32_e32 v63, v46, v52
	v_sub_f32_e32 v64, v47, v52
	v_sub_f32_e32 v65, v48, v52
	v_sub_f32_e32 v66, v49, v52
	v_sub_f32_e32 v67, v50, v52
	v_sub_f32_e32 v83, v51, v52
	v_mov_b32_e32 v37, v36
	v_mov_b32_e32 v38, v36
	v_mov_b32_e32 v39, v36
	v_mov_b32_e32 v40, v36
	v_mov_b32_e32 v41, v36
	v_mov_b32_e32 v42, v36
	v_mov_b32_e32 v43, v36
	v_mov_b32_e32 v44, v36
	v_mov_b32_e32 v45, v36
	v_mov_b32_e32 v46, v36
	v_mov_b32_e32 v47, v36
	v_mov_b32_e32 v48, v36
	v_mov_b32_e32 v49, v36
	v_mov_b32_e32 v50, v36
	v_mov_b32_e32 v51, v36
	v_sub_f32_e32 v20, v20, v52
	v_sub_f32_e32 v21, v21, v52
	s_waitcnt vmcnt(0) lgkmcnt(0)
	s_barrier
	v_sub_f32_e32 v22, v22, v52
	v_sub_f32_e32 v23, v23, v52
	v_sub_f32_e32 v24, v24, v52
	v_sub_f32_e32 v25, v25, v52
	v_sub_f32_e32 v26, v26, v52
	v_sub_f32_e32 v27, v27, v52
	v_sub_f32_e32 v28, v28, v52
	v_sub_f32_e32 v29, v29, v52
	v_sub_f32_e32 v30, v30, v52
	v_sub_f32_e32 v31, v31, v52
	v_sub_f32_e32 v32, v32, v52
	v_sub_f32_e32 v33, v33, v52
	v_sub_f32_e32 v34, v34, v52
	v_sub_f32_e32 v35, v35, v52
	v_exp_f32_e32 v68, v53
	v_exp_f32_e32 v52, v20
	v_exp_f32_e32 v53, v21
	v_lshl_add_u64 v[20:21], v[188:189], 0, s[22:23]
	s_mov_b32 m0, s46
	s_nop 0
	global_load_lds_dwordx4 v[20:21], off
	s_cselect_b32 s1, 0, 0
	s_add_i32 s1, s1, s45
	s_add_i32 s1, s1, 0x8000
	s_mov_b32 m0, s1
	s_nop 0
	global_load_lds_dwordx4 v[190:191], off
	ds_read_b128 v[180:183], v218 offset:8192
	ds_read_b128 v[176:179], v218 offset:8704
	ds_read_b128 v[172:175], v218 offset:10240
	ds_read_b128 v[168:171], v218 offset:10752
	ds_read_b128 v[164:167], v218 offset:12288
	ds_read_b128 v[160:163], v218 offset:12800
	ds_read_b128 v[156:159], v218 offset:14336
	ds_read_b128 v[152:155], v218 offset:14848
	v_exp_f32_e32 v69, v54
	v_exp_f32_e32 v70, v55
	v_exp_f32_e32 v71, v56
	v_exp_f32_e32 v72, v57
	v_exp_f32_e32 v73, v58
	v_exp_f32_e32 v74, v59
	v_exp_f32_e32 v75, v60
	v_exp_f32_e32 v76, v61
	v_exp_f32_e32 v77, v62
	v_exp_f32_e32 v78, v63
	v_exp_f32_e32 v79, v64
	v_exp_f32_e32 v80, v65
	v_exp_f32_e32 v81, v66
	v_exp_f32_e32 v82, v67
	v_exp_f32_e32 v83, v83
	v_exp_f32_e32 v54, v22
	v_exp_f32_e32 v55, v23
	v_exp_f32_e32 v56, v24
	v_exp_f32_e32 v57, v25
	v_exp_f32_e32 v58, v26
	v_exp_f32_e32 v59, v27
	v_exp_f32_e32 v60, v28
	v_exp_f32_e32 v61, v29
	v_exp_f32_e32 v62, v30
	v_exp_f32_e32 v63, v31
	v_exp_f32_e32 v64, v32
	v_exp_f32_e32 v65, v33
	v_exp_f32_e32 v66, v34
	v_exp_f32_e32 v67, v35
	s_waitcnt vmcnt(2) lgkmcnt(0)
	s_barrier
	s_andn2_b64 vcc, exec, s[4:5]
	v_cmp_gt_u32_e64 s[4:5], 32, v1
	s_cbranch_vccnz .LBB0_812
	v_lshlrev_b32_e32 v20, 4, v209
	s_mov_b64 s[10:11], 0xa0000
	v_add_u32_e32 v203, s53, v20
	v_mov_b64_e32 v[34:35], v[18:19]
	s_add_i32 s1, s48, -5
	v_lshl_add_u32 v202, v208, 2, s53
	v_lshl_add_u64 v[192:193], v[84:85], 0, s[22:23]
	v_lshl_add_u64 v[194:195], v[188:189], 0, s[10:11]
	s_movk_i32 s24, 0x4000
	s_movk_i32 s25, 0x2000
	s_mov_b32 s10, 0
	v_mov_b32_e32 v220, 0
	v_mov_b64_e32 v[32:33], v[16:17]
	v_mov_b64_e32 v[30:31], v[14:15]
	v_mov_b64_e32 v[28:29], v[12:13]
	v_mov_b64_e32 v[26:27], v[10:11]
	v_mov_b64_e32 v[24:25], v[8:9]
	v_mov_b64_e32 v[22:23], v[6:7]
	v_mov_b64_e32 v[20:21], v[4:5]
	s_mov_b64 s[98:99], exec
	v_and_b32_e32 v224, 0xffff0000, v36
	v_sub_f32_e32 v225, v224, v36
	v_exp_f32_e32 v225, v225
	v_bfe_i32 v196, v132, 0, 1
	v_mov_b32_e32 v250, 0
	v_mov_b32_e32 v251, 0
	v_mov_b32_e32 v252, 0
	v_mov_b32_e32 v253, 0
	v_mov_b32_e32 v247, 0
	v_mov_b32_e32 v248, 0
	v_mov_b32_e32 v249, 0
	v_mov_b32_e32 v222, 0
	v_mov_b32_e32 v223, 0
	s_mov_b32 exec_hi, 0
	v_mov_b32_e32 v250, 0x3f80
	v_mov_b32_e32 v223, 0xf180
	v_lshrrev_b32_e32 v222, 16, v224
	s_mov_b64 exec, s[98:99]
	v_readfirstlane_b32 s98, v192
	v_readfirstlane_b32 s99, v193
	s_sub_u32 s98, s98, 0x1000000
	s_subb_u32 s99, s99, 0
	v_subrev_u32_e32 v199, s98, v192
	v_subrev_u32_e32 v198, s98, v194
	v_add_u32_e32 v203, 0xfffe0000, v199
	v_add_u32_e32 v202, 0xfffe0000, v198
	v_and_b32_e32 v224, v225, v196
	v_mul_f32_e32 v4, v225, v4
	v_mul_f32_e32 v5, v225, v5
	v_mul_f32_e32 v6, v225, v6
	v_mul_f32_e32 v7, v225, v7
	v_mul_f32_e32 v8, v225, v8
	v_mul_f32_e32 v9, v225, v9
	v_mul_f32_e32 v10, v225, v10
	v_mul_f32_e32 v11, v225, v11
	v_mul_f32_e32 v12, v225, v12
	v_mul_f32_e32 v13, v225, v13
	v_mul_f32_e32 v14, v225, v14
	v_mul_f32_e32 v15, v225, v15
	v_mul_f32_e32 v16, v225, v16
	v_mul_f32_e32 v17, v225, v17
	v_mul_f32_e32 v18, v225, v18
	v_mul_f32_e32 v19, v225, v19
	v_mul_f32_e32 v20, v225, v20
	v_mul_f32_e32 v21, v225, v21
	v_mul_f32_e32 v22, v225, v22
	v_mul_f32_e32 v23, v225, v23
	v_mul_f32_e32 v24, v225, v24
	v_mul_f32_e32 v25, v225, v25
	v_mul_f32_e32 v26, v225, v26
	v_mul_f32_e32 v27, v225, v27
	v_mul_f32_e32 v28, v225, v28
	v_mul_f32_e32 v29, v225, v29
	v_mul_f32_e32 v30, v225, v30
	v_mul_f32_e32 v31, v225, v31
	v_mul_f32_e32 v32, v225, v32
	v_mul_f32_e32 v33, v225, v33
	v_mul_f32_e32 v34, v225, v34
	v_mul_f32_e32 v35, v225, v35
	v_mul_f32_e32 v52, v224, v52
	v_mul_f32_e32 v53, v224, v53
	v_mul_f32_e32 v54, v224, v54
	v_mul_f32_e32 v55, v224, v55
	v_mul_f32_e32 v56, v224, v56
	v_mul_f32_e32 v57, v224, v57
	v_mul_f32_e32 v58, v224, v58
	v_mul_f32_e32 v59, v224, v59
	v_mul_f32_e32 v60, v224, v60
	v_mul_f32_e32 v61, v224, v61
	v_mul_f32_e32 v62, v224, v62
	v_mul_f32_e32 v63, v224, v63
	v_mul_f32_e32 v64, v224, v64
	v_mul_f32_e32 v65, v224, v65
	v_mul_f32_e32 v66, v224, v66
	v_mul_f32_e32 v67, v224, v67
	v_mul_f32_e32 v68, v224, v68
	v_mul_f32_e32 v69, v224, v69
	v_mul_f32_e32 v70, v224, v70
	v_mul_f32_e32 v71, v224, v71
	v_mul_f32_e32 v72, v224, v72
	v_mul_f32_e32 v73, v224, v73
	v_mul_f32_e32 v74, v224, v74
	v_mul_f32_e32 v75, v224, v75
	v_mul_f32_e32 v76, v224, v76
	v_mul_f32_e32 v77, v224, v77
	v_mul_f32_e32 v78, v224, v78
	v_mul_f32_e32 v79, v224, v79
	v_mul_f32_e32 v80, v224, v80
	v_mul_f32_e32 v81, v224, v81
	v_mul_f32_e32 v82, v224, v82
	v_mul_f32_e32 v83, v224, v83
	v_mul_f32_e32 v220, v225, v220
	v_bfe_i32 v196, v132, 1, 1
	v_bfi_b32 v246, v196, v222, v223
	s_mov_b32 s101, 2
	s_nop 1
	v_mfma_f32_32x32x16_bf16 v[36:51], v[250:253], v[246:249], 0
	s_branch .LBB0_798

.LBB0_798:
	v_add_u32_e32 v197, s10, v219
	ds_read_b64_tr_b16 v[184:185], v197 offset:24576
	ds_read_b64_tr_b16 v[186:187], v197 offset:25088
	v_mfma_f32_32x32x16_bf16 v[100:115], v[180:183], v[116:119], v[36:51]
	v_add_f32_e32 v84, v68, v69
	v_add_f32_e32 v84, v70, v84
	v_add_f32_e32 v84, v71, v84
	v_cvt_pk_bf16_f32 v148, v68, v69
	v_add_f32_e32 v84, v72, v84
	v_cvt_pk_bf16_f32 v149, v70, v71
	v_add_f32_e32 v84, v73, v84
	ds_read_b64_tr_b16 v[180:181], v197 offset:28672
	ds_read_b64_tr_b16 v[182:183], v197 offset:29184
	v_add_f32_e32 v68, v74, v84
	v_mfma_f32_32x32x16_bf16 v[84:99], v[176:179], v[116:119], v[36:51]
	v_add_f32_e32 v68, v75, v68
	v_add_f32_e32 v68, v76, v68
	v_add_f32_e32 v136, v77, v68
	v_cvt_pk_bf16_f32 v150, v72, v73
	v_cvt_pk_bf16_f32 v151, v74, v75
	ds_read_b64_tr_b16 v[68:69], v197 offset:25600
	ds_read_b64_tr_b16 v[70:71], v197 offset:26112
	v_mfma_f32_32x32x16_bf16 v[100:115], v[172:175], v[120:123], v[100:115]
	v_add_f32_e32 v72, v78, v136
	v_add_f32_e32 v72, v79, v72
	v_add_f32_e32 v72, v80, v72
	v_add_f32_e32 v136, v81, v72
	v_cvt_pk_bf16_f32 v144, v76, v77
	v_cvt_pk_bf16_f32 v145, v78, v79
	ds_read_b64_tr_b16 v[72:73], v197 offset:29696
	ds_read_b64_tr_b16 v[74:75], v197 offset:30208
	v_mfma_f32_32x32x16_bf16 v[84:99], v[168:171], v[120:123], v[84:99]
	v_add_f32_e32 v76, v82, v136
	v_add_f32_e32 v76, v83, v76
	v_add_f32_e32 v76, v52, v76
	v_add_f32_e32 v136, v53, v76
	v_cvt_pk_bf16_f32 v146, v80, v81
	v_cvt_pk_bf16_f32 v147, v82, v83
	ds_read_b64_tr_b16 v[76:77], v197 offset:26624
	ds_read_b64_tr_b16 v[78:79], v197 offset:27136
	v_mfma_f32_32x32x16_bf16 v[100:115], v[164:167], v[124:127], v[100:115]
	v_add_f32_e32 v80, v54, v136
	v_add_f32_e32 v80, v55, v80
	v_cvt_pk_bf16_f32 v140, v52, v53
	v_add_f32_e32 v80, v56, v80
	v_cvt_pk_bf16_f32 v141, v54, v55
	v_add_f32_e32 v80, v57, v80
	ds_read_b64_tr_b16 v[52:53], v197 offset:30720
	ds_read_b64_tr_b16 v[54:55], v197 offset:31232
	v_mfma_f32_32x32x16_bf16 v[84:99], v[160:163], v[124:127], v[84:99]
	v_add_f32_e32 v80, v58, v80
	v_add_f32_e32 v80, v59, v80
	v_cvt_pk_bf16_f32 v142, v56, v57
	v_add_f32_e32 v80, v60, v80
	v_cvt_pk_bf16_f32 v143, v58, v59
	v_add_f32_e32 v80, v61, v80
	ds_read_b64_tr_b16 v[56:57], v197 offset:27648
	ds_read_b64_tr_b16 v[58:59], v197 offset:28160
	v_mfma_f32_32x32x16_bf16 v[100:115], v[156:159], v[128:131], v[100:115]
	v_add_f32_e32 v80, v62, v80
	v_add_f32_e32 v80, v63, v80
	v_cvt_pk_bf16_f32 v136, v60, v61
	v_add_f32_e32 v80, v64, v80
	v_cvt_pk_bf16_f32 v137, v62, v63
	v_add_f32_e32 v80, v65, v80
	ds_read_b64_tr_b16 v[60:61], v197 offset:31744
	ds_read_b64_tr_b16 v[62:63], v197 offset:32256
	v_mfma_f32_32x32x16_bf16 v[84:99], v[152:155], v[128:131], v[84:99]
	v_add_f32_e32 v80, v66, v80
	v_cvt_pk_bf16_f32 v138, v64, v65
	v_add_f32_e32 v80, v67, v80
	v_cvt_pk_bf16_f32 v139, v66, v67
	s_add_i32 s10, s25, s46
	s_mov_b32 m0, s10
	s_nop 0
	global_load_lds_dwordx4 v202, s[98:99]
	s_add_i32 s10, s24, s47
	s_mov_b32 m0, s10
	s_nop 0
	global_load_lds_dwordx4 v203, s[98:99]
	v_add_f32_e32 v204, v220, v80

.LBB0_801:
	v_add_u32_e32 v197, s25, v219
	ds_read_b64_tr_b16 v[152:153], v197 offset:24576
	ds_read_b64_tr_b16 v[154:155], v197 offset:25088
	v_mfma_f32_32x32x16_bf16 v[68:83], v[64:67], v[116:119], v[36:51]
	v_add_f32_e32 v52, v100, v101
	v_add_f32_e32 v52, v102, v52
	v_add_f32_e32 v52, v103, v52
	v_cvt_pk_bf16_f32 v148, v100, v101
	v_add_f32_e32 v52, v104, v52
	v_cvt_pk_bf16_f32 v149, v102, v103
	v_add_f32_e32 v52, v105, v52
	ds_read_b64_tr_b16 v[156:157], v197 offset:28672
	ds_read_b64_tr_b16 v[158:159], v197 offset:29184
	v_add_f32_e32 v52, v106, v52
	v_add_f32_e32 v52, v107, v52
	v_add_f32_e32 v52, v108, v52
	v_add_f32_e32 v136, v109, v52
	v_mfma_f32_32x32x16_bf16 v[52:67], v[180:183], v[116:119], v[36:51]
	v_cvt_pk_bf16_f32 v150, v104, v105
	v_cvt_pk_bf16_f32 v151, v106, v107
	ds_read_b64_tr_b16 v[100:101], v197 offset:25600
	ds_read_b64_tr_b16 v[102:103], v197 offset:26112
	v_mfma_f32_32x32x16_bf16 v[68:83], v[184:187], v[120:123], v[68:83]
	v_add_f32_e32 v104, v110, v136
	v_add_f32_e32 v104, v111, v104
	v_add_f32_e32 v104, v112, v104
	v_add_f32_e32 v136, v113, v104
	v_cvt_pk_bf16_f32 v144, v108, v109
	v_cvt_pk_bf16_f32 v145, v110, v111
	ds_read_b64_tr_b16 v[104:105], v197 offset:29696
	ds_read_b64_tr_b16 v[106:107], v197 offset:30208
	v_mfma_f32_32x32x16_bf16 v[52:67], v[176:179], v[120:123], v[52:67]
	v_add_f32_e32 v108, v114, v136
	v_add_f32_e32 v108, v115, v108
	v_add_f32_e32 v108, v84, v108
	v_add_f32_e32 v136, v85, v108
	v_cvt_pk_bf16_f32 v146, v112, v113
	v_cvt_pk_bf16_f32 v147, v114, v115
	ds_read_b64_tr_b16 v[108:109], v197 offset:26624
	ds_read_b64_tr_b16 v[110:111], v197 offset:27136
	v_mfma_f32_32x32x16_bf16 v[68:83], v[172:175], v[124:127], v[68:83]
	v_add_f32_e32 v112, v86, v136
	v_add_f32_e32 v112, v87, v112
	v_cvt_pk_bf16_f32 v140, v84, v85
	v_add_f32_e32 v112, v88, v112
	v_cvt_pk_bf16_f32 v141, v86, v87
	v_add_f32_e32 v112, v89, v112
	ds_read_b64_tr_b16 v[84:85], v197 offset:30720
	ds_read_b64_tr_b16 v[86:87], v197 offset:31232
	v_mfma_f32_32x32x16_bf16 v[52:67], v[168:171], v[124:127], v[52:67]
	v_add_f32_e32 v112, v90, v112
	v_add_f32_e32 v112, v91, v112
	v_cvt_pk_bf16_f32 v142, v88, v89
	v_add_f32_e32 v112, v92, v112
	v_cvt_pk_bf16_f32 v143, v90, v91
	v_add_f32_e32 v112, v93, v112
	ds_read_b64_tr_b16 v[88:89], v197 offset:27648
	ds_read_b64_tr_b16 v[90:91], v197 offset:28160
	v_mfma_f32_32x32x16_bf16 v[68:83], v[164:167], v[128:131], v[68:83]
	v_add_f32_e32 v112, v94, v112
	v_add_f32_e32 v112, v95, v112
	v_cvt_pk_bf16_f32 v136, v92, v93
	v_add_f32_e32 v112, v96, v112
	v_cvt_pk_bf16_f32 v137, v94, v95
	v_add_f32_e32 v112, v97, v112
	ds_read_b64_tr_b16 v[92:93], v197 offset:31744
	ds_read_b64_tr_b16 v[94:95], v197 offset:32256
	v_mfma_f32_32x32x16_bf16 v[52:67], v[160:163], v[128:131], v[52:67]
	v_add_f32_e32 v112, v98, v112
	v_cvt_pk_bf16_f32 v138, v96, v97
	v_add_f32_e32 v112, v99, v112
	v_cvt_pk_bf16_f32 v139, v98, v99
	v_add_f32_e32 v220, v204, v112
	s_add_i32 s10, s24, s46
	s_mov_b32 m0, s10
	s_nop 0
	global_load_lds_dwordx4 v198, s[98:99]
	s_add_i32 s10, s54, s47
	s_mov_b32 m0, s10
	s_nop 0
	global_load_lds_dwordx4 v199, s[98:99]
.LBB0_802:
	s_waitcnt lgkmcnt(14)
	v_mfma_f32_32x32x16_bf16 v[20:35], v[148:151], v[152:155], v[20:35]
	v_exp_f32_e32 v68, v68
	v_exp_f32_e32 v69, v69
	v_exp_f32_e32 v70, v70
	v_exp_f32_e32 v71, v71
	s_waitcnt lgkmcnt(12)
	v_mfma_f32_32x32x16_bf16 v[4:19], v[148:151], v[156:159], v[4:19]
	v_exp_f32_e32 v72, v72
	v_exp_f32_e32 v73, v73
	v_exp_f32_e32 v74, v74
	v_exp_f32_e32 v75, v75
	v_add_u32_e32 v96, s54, v218
	ds_read_b128 v[180:183], v96
	ds_read_b128 v[176:179], v96 offset:512
	s_waitcnt lgkmcnt(12)
	v_mfma_f32_32x32x16_bf16 v[20:35], v[144:147], v[100:103], v[20:35]
	v_exp_f32_e32 v76, v76
	v_exp_f32_e32 v77, v77
	v_exp_f32_e32 v78, v78
	v_exp_f32_e32 v79, v79
	ds_read_b128 v[172:175], v96 offset:2048
	ds_read_b128 v[168:171], v96 offset:2560
	s_waitcnt lgkmcnt(12)
	v_mfma_f32_32x32x16_bf16 v[4:19], v[144:147], v[104:107], v[4:19]
	v_exp_f32_e32 v80, v80
	v_exp_f32_e32 v81, v81
	v_exp_f32_e32 v82, v82
	v_exp_f32_e32 v83, v83
	ds_read_b128 v[164:167], v96 offset:4096
	ds_read_b128 v[160:163], v96 offset:4608
	s_waitcnt lgkmcnt(12)
	v_mfma_f32_32x32x16_bf16 v[20:35], v[140:143], v[108:111], v[20:35]
	v_exp_f32_e32 v52, v52
	v_exp_f32_e32 v53, v53
	v_exp_f32_e32 v54, v54
	v_exp_f32_e32 v55, v55
	ds_read_b128 v[156:159], v96 offset:6144
	ds_read_b128 v[152:155], v96 offset:6656
	s_waitcnt lgkmcnt(12)
	v_mfma_f32_32x32x16_bf16 v[4:19], v[140:143], v[84:87], v[4:19]
	v_exp_f32_e32 v56, v56
	v_exp_f32_e32 v57, v57
	v_exp_f32_e32 v58, v58
	v_exp_f32_e32 v59, v59
	s_waitcnt lgkmcnt(10)
	v_mfma_f32_32x32x16_bf16 v[20:35], v[136:139], v[88:91], v[20:35]
	v_exp_f32_e32 v60, v60
	v_exp_f32_e32 v61, v61
	v_exp_f32_e32 v62, v62
	v_exp_f32_e32 v63, v63
	v_bfe_i32 v196, v132, s101, 1
	v_bfi_b32 v246, v196, v222, v223
	s_waitcnt lgkmcnt(8)
	v_mfma_f32_32x32x16_bf16 v[4:19], v[136:139], v[92:95], v[4:19]
	v_exp_f32_e32 v64, v64
	v_exp_f32_e32 v65, v65
	v_exp_f32_e32 v66, v66
	v_exp_f32_e32 v67, v67
	v_mfma_f32_32x32x16_bf16 v[36:51], v[250:253], v[246:249], 0
	s_add_i32 s101, s101, 1
	s_add_i32 s0, s0, 2
	s_add_i32 s10, s54, 0x2000
	s_cmpk_lg_i32 s54, 0x4000
	s_cselect_b32 s42, s10, 0
	s_add_u32 s98, s98, s80
	s_addc_u32 s99, s99, s81
	s_cmp_ge_i32 s0, s1
	s_cbranch_scc1 .Lattn0_exit
	s_mov_b32 s10, s24
	s_mov_b32 s25, s54
	s_mov_b32 s24, s42
	s_branch .Lattn0_head
.Lattn0_exit:
	v_mov_b32_e32 v193, s99
	v_mov_b32_e32 v195, s99
	v_add_co_u32_e32 v192, vcc, s98, v199
	v_addc_co_u32_e32 v193, vcc, 0, v193, vcc
	v_add_co_u32_e32 v194, vcc, s98, v198
	v_addc_co_u32_e32 v195, vcc, 0, v195, vcc
	s_sub_i32 s100, s101, 2
	v_mov_b32_e32 v246, v222
	v_alignbit_b32 v132, v133, v132, s100
	v_alignbit_b32 v133, v134, v133, s100
	v_alignbit_b32 v134, v135, v134, s100
	v_lshrrev_b32_e32 v135, s100, v135
	v_mfma_f32_32x32x16_bf16 v[36:51], v[250:253], v[246:249], 0
	s_nop 7
	s_nop 3
	s_waitcnt vmcnt(2) lgkmcnt(0)
	s_barrier
	s_branch .LBB0_813
